# scan phase: the 128 long (latent) items statically assigned to workgroups 0..15 of each XCD so that no two share a CU; the short prompt items handed out by the ticket counter
# speedup vs baseline: 1.0103x; 1.0103x over previous
.Lhw_bar_scope:
	s_and_b32 s9, s82, 7
	s_lshl_b32 s9, s9, 4
	s_add_i32 s9, s9, s83
	s_add_i32 s9, s9, 1
	s_cmpk_lt_u32 s83, 16
	s_cselect_b32 s9, s9, 0
	v_writelane_b32 v246, s9, 45
	v_readlane_b32 s2, v246, 26
	s_and_b32 s9, s88, 1
	s_lshl_b32 s8, s9, 8
	s_xor_b32 s9, s9, 1
	s_lshl_b32 s9, s9, 6
	s_or_b32 s8, s8, s9
	s_or_b32 s8, s8, 0xe1e
	s_lshr_b32 s8, s8, s2
	v_readlane_b32 s6, v246, 41
	s_and_b32 s8, s8, 1
	s_and_b32 s8, s8, s6
	v_writelane_b32 v246, s8, 42
	s_waitcnt vmcnt(0)
	s_barrier
	v_mov_b32 v0, v194
	s_nop 0
	v_cmp_eq_u32_e32 vcc, 0, v0
	s_and_saveexec_b64 s[0:1], vcc
	s_cbranch_execz .LBB0_108
	s_waitcnt vmcnt(0) expcnt(0) lgkmcnt(0)
	ds_read_b32 v3, v1
	ds_read_b32 v0, v1 offset:4
	s_waitcnt lgkmcnt(1)
	v_cmp_ne_u32_e32 vcc, 0, v3
	s_cbranch_vccnz .LBB0_71
	s_mov_b32 s2, 1
	s_branch .LBB0_54

.LBB0_166:
	s_barrier
	v_readlane_b32 s12, v246, 45
	s_cmp_eq_u32 s12, 0
	s_cbranch_scc1 .Lhw_scan_fetch
	s_add_i32 s2, s12, -1
	s_mov_b32 s12, 0
	s_nop 0
	v_writelane_b32 v246, s12, 45
	s_branch .Lhw_scan_have_item
.Lhw_scan_fetch:
	s_and_saveexec_b64 s[14:15], s[40:41]
	s_cbranch_execz .LBB0_170
	s_mov_b64 s[18:19], exec
	v_mbcnt_lo_u32_b32 v0, s18, 0
	v_mbcnt_hi_u32_b32 v0, s19, v0
	v_cmp_eq_u32_e32 vcc, 0, v0
	s_and_saveexec_b64 s[16:17], vcc
	s_cbranch_execz .LBB0_169
	s_bcnt1_i32_b64 s2, s[18:19]
	v_readlane_b32 s12, v246, 33
	v_mov_b32_e32 v2, s2
	v_readlane_b32 s13, v246, 34
	s_nop 4
	global_atomic_add v2, v1, v2, s[12:13] sc0

.LBB0_170:
	s_or_b64 exec, exec, s[14:15]
	s_waitcnt lgkmcnt(0)
	s_barrier
	ds_read_b32 v0, v204 offset:47360
	s_movk_i32 s12, 0x1ff
	s_mov_b64 s[14:15], -1
	s_waitcnt lgkmcnt(0)
	v_cmp_lt_i32_e32 vcc, s12, v0
	v_readfirstlane_b32 s2, v0
	s_cbranch_vccnz .LBB0_165
	s_addk_i32 s2, 0x80
.Lhw_scan_have_item:
	s_cmpk_lt_i32 s2, 0x80
	s_cselect_b64 s[84:85], -1, 0
	s_cmpk_gt_i32 s2, 0x7f
	s_cselect_b64 s[14:15], -1, 0
	s_mov_b64 s[16:17], -1
	s_and_b64 vcc, exec, s[14:15]
	s_cbranch_vccz .LBB0_173
	s_add_i32 s12, s2, 0xffffff80
	s_bfe_u32 s24, s12, 0x40004
	s_lshr_b32 s20, s12, 8
	s_mov_b64 s[16:17], 0
